# 256sq GEMM phases: touch first two K-tiles of unit 0 (A and B rows) before epi_tables to overlap cold-start latency
# baseline (speedup 1.0000x reference)
.LBB0_111:
	s_add_i32 s0, s74, -2
	s_mul_hi_i32 s1, s0, 0x2aaaaaab
	s_lshr_b32 s2, s1, 31
	s_add_i32 s28, s1, s2
	s_mov_b32 s2, s28
	v_writelane_b32 v255, s2, 36
	s_mul_i32 s1, s28, 6
	s_mov_b64 s[66:67], 0
	v_writelane_b32 v255, s3, 37
	s_sub_i32 s2, s0, s1
	v_writelane_b32 v255, s2, 38
	s_cmp_lt_i32 s2, 2
	s_mov_b64 s[2:3], 0
	v_writelane_b32 v255, s2, 39
	s_mov_b64 s[0:1], -1
	s_mov_b32 s91, s74
	v_writelane_b32 v255, s3, 40
	s_cbranch_scc1 .LBB0_386
	v_readlane_b32 s0, v255, 38
	s_cmp_gt_i32 s0, 2
	s_cbranch_scc0 .LBB0_169
	s_cmp_gt_i32 s0, 3
	s_cbranch_scc0 .LBB0_170
	s_cmp_eq_u32 s0, 4
	s_mov_b64 s[0:1], -1
	s_cbranch_scc0 .LBB0_172
	s_ashr_i32 s33, s30, 31
	s_cmpk_lt_i32 s30, 0x2c0
	s_waitcnt lgkmcnt(0)
	v_mov_b32_e32 v1, v228
	s_cselect_b64 s[0:1], -1, 0
	s_cmpk_gt_i32 s30, 0x2bf
	s_cbranch_scc1 .LBB0_151
	s_and_b32 s36, s30, 7
	s_lshl_b32 s36, s36, 2
	s_bfe_u32 s37, s30, 0x20003
	s_add_u32 s36, s36, s37
	s_lshr_b32 s37, s30, 5
	v_readlane_b32 s38, v255, 36
	v_readlane_b32 s40, v254, 63
	v_readlane_b32 s41, v255, 0
	v_readfirstlane_b32 s42, v228
	v_and_b32_e32 v4, 0xff, v228
	v_lshlrev_b32_e32 v4, 11, v4
	s_nop 3
	s_mul_i32 s39, s38, 0xb00000
	s_add_u32 s40, s40, s39
	s_addc_u32 s41, s41, 0
	s_lshl_b32 s37, s37, 19
	s_add_u32 s40, s40, s37
	s_addc_u32 s41, s41, 0
	s_lshl_b32 s36, s36, 19
	s_add_u32 s38, s14, s36
	s_addc_u32 s39, s15, 0
	s_cmp_lt_u32 s42, 0x100
	s_cselect_b32 s38, s38, s40
	s_cselect_b32 s39, s39, s41
	global_load_dword v6, v4, s[38:39]
	global_load_dword v7, v4, s[38:39] offset:128
	v_readfirstlane_b32 s36, v228
	s_nop 3
	s_cmp_lt_u32 s36, 0x100
	s_cbranch_scc0 .Lepi4_bias
	s_mov_b32 s28, s30
	s_mov_b32 s29, 0
	v_lshlrev_b32_e32 v0, 7, v228
	v_lshl_add_u32 v3, v228, 2, v246

.LBB0_677:
	s_and_b64 vcc, exec, s[66:67]
	s_cbranch_vccz .LBB0_767
	v_readlane_b32 s0, v255, 36
	v_readlane_b32 s1, v255, 37
	s_ashr_i32 s1, s0, 31
	s_ashr_i32 s33, s30, 31
	v_writelane_b32 v255, s0, 36
	s_cmpk_lt_i32 s30, 0x160
	s_waitcnt lgkmcnt(0)
	v_mov_b32_e32 v1, v228
	v_writelane_b32 v255, s1, 37
	s_cselect_b64 s[2:3], -1, 0
	s_cmpk_gt_i32 s30, 0x15f
	s_cbranch_scc1 .LBB0_714
	s_and_b32 s36, s30, 7
	s_lshl_b32 s36, s36, 2
	s_bfe_u32 s37, s30, 0x20003
	s_add_u32 s36, s36, s37
	s_lshr_b32 s37, s30, 5
	v_readlane_b32 s38, v255, 36
	v_readlane_b32 s40, v254, 59
	v_readlane_b32 s41, v254, 60
	v_readfirstlane_b32 s42, v228
	v_and_b32_e32 v4, 0xff, v228
	v_lshlrev_b32_e32 v4, 11, v4
	s_nop 3
	s_mul_i32 s39, s38, 0x580000
	s_add_u32 s40, s40, s39
	s_addc_u32 s41, s41, 0
	s_lshl_b32 s37, s37, 19
	s_add_u32 s40, s40, s37
	s_addc_u32 s41, s41, 0
	s_lshl_b32 s36, s36, 19
	s_add_u32 s38, s14, s36
	s_addc_u32 s39, s15, 0
	s_cmp_lt_u32 s42, 0x100
	s_cselect_b32 s38, s38, s40
	s_cselect_b32 s39, s39, s41
	global_load_dword v6, v4, s[38:39]
	global_load_dword v7, v4, s[38:39] offset:128
	v_readfirstlane_b32 s36, v228
	s_nop 3
	s_cmp_lt_u32 s36, 0x100
	s_cbranch_scc0 .Lepi0_bias
	s_mov_b32 s28, s30
	s_mov_b32 s29, 0
	v_lshlrev_b32_e32 v0, 7, v228
	v_lshl_add_u32 v3, v228, 2, v246
